# v13: XC setup - both LDS staging blocks' global loads in flight together (second block's loads issued before the first block's wait), on top of v10
# baseline (speedup 1.0000x reference)
; #define LAS __attribute__((address_space(3)))
; DEV void xc_gates_phase(LAS char* shm, const bf16_t* mi, bf16_t* xc, const bf16_t* WfT, const float* cw, const float* cb, float* gpart  ) {
;     ...
;     for (int i = tid; i < 2 * 8 * 128; i += 512) {
;         const int rowi = i >> 7, pc = i & 127;
;         const uint4 v = *(const uint4*)(WfT + (size_t)((rowi >> 3) * 16 + (rowi & 7)) * 1024 + pc * 8);
;         *(LAS u32x4*)(shm + rowi * WRS + pc * 16) = (u32x4){v.x, v.y, v.z, v.w};
;     }
;     for (int i = tid; i < 5 * 256; i += 512) {
;         const float4 v = (i < 1024) ? *(const float4*)(cw + i * 4) : *(const float4*)(cb + (i - 1024) * 4);
;         *(LAS f32x4*)(shm + CWL + i * 16) = (f32x4){v.x, v.y, v.z, v.w};
;     }
.LBB0_315:
	s_movk_i32 s20, 0x810
	v_add_u32_e32 v100, 0, v5
	v_ashrrev_i32_e32 v101, 7, v100
	v_ashrrev_i32_e32 v109, 6, v100
	v_and_b32_e32 v102, 7, v101
	v_and_or_b32 v102, v109, -16, v102
	v_ashrrev_i32_e32 v103, 31, v102
	v_lshlrev_b64 v[102:103], 11, v[102:103]
	v_lshl_add_u64 v[102:103], v[2:3], 0, v[102:103]
	global_load_dwordx4 v[104:107], v[102:103], off
	v_mad_u32_u24 v108, v101, s20, v4
	v_add_u32_e32 v112, 512, v5
	v_ashrrev_i32_e32 v113, 7, v112
	v_ashrrev_i32_e32 v121, 6, v112
	v_and_b32_e32 v114, 7, v113
	v_and_or_b32 v114, v121, -16, v114
	v_ashrrev_i32_e32 v115, 31, v114
	v_lshlrev_b64 v[114:115], 11, v[114:115]
	v_lshl_add_u64 v[114:115], v[2:3], 0, v[114:115]
	global_load_dwordx4 v[116:119], v[114:115], off
	v_mad_u32_u24 v120, v113, s20, v4
	v_add_u32_e32 v124, 1024, v5
	v_ashrrev_i32_e32 v125, 7, v124
	v_ashrrev_i32_e32 v133, 6, v124
	v_and_b32_e32 v126, 7, v125
	v_and_or_b32 v126, v133, -16, v126
	v_ashrrev_i32_e32 v127, 31, v126
	v_lshlrev_b64 v[126:127], 11, v[126:127]
	v_lshl_add_u64 v[126:127], v[2:3], 0, v[126:127]
	global_load_dwordx4 v[128:131], v[126:127], off
	v_mad_u32_u24 v132, v125, s20, v4
	v_add_u32_e32 v136, 1536, v5
	v_ashrrev_i32_e32 v137, 7, v136
	v_ashrrev_i32_e32 v145, 6, v136
	v_and_b32_e32 v138, 7, v137
	v_and_or_b32 v138, v145, -16, v138
	v_ashrrev_i32_e32 v139, 31, v138
	v_lshlrev_b64 v[138:139], 11, v[138:139]
	v_lshl_add_u64 v[138:139], v[2:3], 0, v[138:139]
	global_load_dwordx4 v[140:143], v[138:139], off
	v_mad_u32_u24 v144, v137, s20, v4
.LBB0_316:
	s_or_b64 exec, exec, s[0:1]
	s_movk_i32 s0, 0x500
	v_cmp_gt_i32_e32 vcc, s0, v5
	s_and_saveexec_b64 s[0:1], vcc
	s_cbranch_execz .LBB0_319
	v_lshl_add_u32 v0, v5, 4, 0
	s_movk_i32 s12, 0xc000
	v_add_u32_e32 v4, 0x8100, v0
	v_lshlrev_b32_e32 v2, 2, v5
	s_mov_b64 s[10:11], 0
	s_movk_i32 s2, 0x400
	v_mov_b32_e32 v7, 0
	s_mov_b32 s13, -1
	s_movk_i32 s19, 0x2ff
	v_mov_b32_e32 v8, v5
.LBB0_318:
	v_ashrrev_i32_e32 v3, 31, v2
	v_lshl_add_u64 v[150:151], v[2:3], 2, s[6:7]
	global_load_dwordx4 v[152:155], v[150:151], off
	s_mov_b64 s[20:21], 0x2000
	v_lshl_add_u64 v[156:157], v[150:151], 0, s[20:21]
	global_load_dwordx4 v[158:161], v[156:157], off
	v_cmp_gt_i32_e32 vcc, 0x100, v5
	s_and_saveexec_b64 s[20:21], vcc
	v_add_u32_e32 v166, 0x1000, v2
	v_mov_b32_e32 v167, 0
	v_lshl_add_u64 v[156:157], v[166:167], 2, s[8:9]
	v_lshl_add_u64 v[156:157], v[156:157], 0, s[12:13]
	global_load_dwordx4 v[162:165], v[156:157], off
	s_or_b64 exec, exec, s[20:21]
	s_waitcnt vmcnt(2)
	ds_write_b128 v108, v[104:107]
	ds_write_b128 v120, v[116:119]
	ds_write_b128 v132, v[128:131]
	ds_write_b128 v144, v[140:143]
	s_waitcnt vmcnt(0)
	ds_write_b128 v4, v[152:155]
	ds_write_b128 v4, v[158:161] offset:8192
	s_and_saveexec_b64 s[20:21], vcc
	ds_write_b128 v4, v[162:165] offset:16384
	s_or_b64 exec, exec, s[20:21]

; #define LAS __attribute__((address_space(3)))
; DEV void xc_gates_phase(LAS char* shm, const bf16_t* mi, bf16_t* xc, const bf16_t* WfT, const float* cw, const float* cb, float* gpart  ) {
;     ...
;     for (int i = tid; i < 2 * 8 * 128; i += 512) {
;         const int rowi = i >> 7, pc = i & 127;
;         const uint4 v = *(const uint4*)(WfT + (size_t)((rowi >> 3) * 16 + (rowi & 7)) * 1024 + pc * 8);
;         *(LAS u32x4*)(shm + rowi * WRS + pc * 16) = (u32x4){v.x, v.y, v.z, v.w};
;     }
;     for (int i = tid; i < 5 * 256; i += 512) {
;         const float4 v = (i < 1024) ? *(const float4*)(cw + i * 4) : *(const float4*)(cb + (i - 1024) * 4);
;         *(LAS f32x4*)(shm + CWL + i * 16) = (f32x4){v.x, v.y, v.z, v.w};
;     }
.LBB0_1170:
	s_movk_i32 s20, 0x810
	v_add_u32_e32 v100, 0, v5
	v_ashrrev_i32_e32 v101, 7, v100
	v_ashrrev_i32_e32 v109, 6, v100
	v_and_b32_e32 v102, 7, v101
	v_and_or_b32 v102, v109, -16, v102
	v_ashrrev_i32_e32 v103, 31, v102
	v_lshlrev_b64 v[102:103], 11, v[102:103]
	v_lshl_add_u64 v[102:103], v[2:3], 0, v[102:103]
	global_load_dwordx4 v[104:107], v[102:103], off
	v_mad_u32_u24 v108, v101, s20, v4
	v_add_u32_e32 v112, 512, v5
	v_ashrrev_i32_e32 v113, 7, v112
	v_ashrrev_i32_e32 v121, 6, v112
	v_and_b32_e32 v114, 7, v113
	v_and_or_b32 v114, v121, -16, v114
	v_ashrrev_i32_e32 v115, 31, v114
	v_lshlrev_b64 v[114:115], 11, v[114:115]
	v_lshl_add_u64 v[114:115], v[2:3], 0, v[114:115]
	global_load_dwordx4 v[116:119], v[114:115], off
	v_mad_u32_u24 v120, v113, s20, v4
	v_add_u32_e32 v124, 1024, v5
	v_ashrrev_i32_e32 v125, 7, v124
	v_ashrrev_i32_e32 v133, 6, v124
	v_and_b32_e32 v126, 7, v125
	v_and_or_b32 v126, v133, -16, v126
	v_ashrrev_i32_e32 v127, 31, v126
	v_lshlrev_b64 v[126:127], 11, v[126:127]
	v_lshl_add_u64 v[126:127], v[2:3], 0, v[126:127]
	global_load_dwordx4 v[128:131], v[126:127], off
	v_mad_u32_u24 v132, v125, s20, v4
	v_add_u32_e32 v136, 1536, v5
	v_ashrrev_i32_e32 v137, 7, v136
	v_ashrrev_i32_e32 v145, 6, v136
	v_and_b32_e32 v138, 7, v137
	v_and_or_b32 v138, v145, -16, v138
	v_ashrrev_i32_e32 v139, 31, v138
	v_lshlrev_b64 v[138:139], 11, v[138:139]
	v_lshl_add_u64 v[138:139], v[2:3], 0, v[138:139]
	global_load_dwordx4 v[140:143], v[138:139], off
	v_mad_u32_u24 v144, v137, s20, v4
.LBB0_1171:
	s_or_b64 exec, exec, s[0:1]
	s_movk_i32 s0, 0x500
	v_cmp_gt_i32_e32 vcc, s0, v5
	s_and_saveexec_b64 s[0:1], vcc
	s_cbranch_execz .LBB0_1174
	s_add_u32 s8, s2, 0x4000
	v_lshl_add_u32 v0, v5, 4, 0
	s_movk_i32 s12, 0xd000
	s_addc_u32 s9, s10, 0
	v_add_u32_e32 v4, 0x8100, v0
	v_lshlrev_b32_e32 v2, 2, v5
	s_mov_b64 s[10:11], 0
	s_movk_i32 s2, 0x400
	v_mov_b32_e32 v7, 0
	s_mov_b32 s13, -1
	s_movk_i32 s19, 0x2ff
	v_mov_b32_e32 v8, v5
.LBB0_1173:
	v_ashrrev_i32_e32 v3, 31, v2
	v_lshl_add_u64 v[150:151], v[2:3], 2, s[8:9]
	global_load_dwordx4 v[152:155], v[150:151], off
	s_mov_b64 s[20:21], 0x2000
	v_lshl_add_u64 v[156:157], v[150:151], 0, s[20:21]
	global_load_dwordx4 v[158:161], v[156:157], off
	v_cmp_gt_i32_e32 vcc, 0x100, v5
	s_and_saveexec_b64 s[20:21], vcc
	v_add_u32_e32 v166, 0x1000, v2
	v_mov_b32_e32 v167, 0
	v_lshl_add_u64 v[156:157], v[166:167], 2, s[4:5]
	v_lshl_add_u64 v[156:157], v[156:157], 0, s[12:13]
	global_load_dwordx4 v[162:165], v[156:157], off
	s_or_b64 exec, exec, s[20:21]
	s_waitcnt vmcnt(2)
	ds_write_b128 v108, v[104:107]
	ds_write_b128 v120, v[116:119]
	ds_write_b128 v132, v[128:131]
	ds_write_b128 v144, v[140:143]
	s_waitcnt vmcnt(0)
	ds_write_b128 v4, v[152:155]
	ds_write_b128 v4, v[158:161] offset:8192
	s_and_saveexec_b64 s[20:21], vcc
	ds_write_b128 v4, v[162:165] offset:16384
	s_or_b64 exec, exec, s[20:21]
